# deleted 4 redundant lgkmcnt(0) at the heads of the K-loop MFMA blocks
# speedup vs baseline: 1.0012x; 1.0012x over previous
; #define PG8_STAGE(bufoff, gbase, voff) do { _Pragma("unroll") for (int _i = 0; _i < 2; ++_i) \
;         __builtin_amdgcn_global_load_lds((const unsigned*)((const char*)(gbase) + (voff)[_i]), (PG8_LAS unsigned*)(lds + (bufoff) + ldsw + _i * 8192), 16, 0, 0); } while (0)
; #define PG8_LDA(dst, b, h) do { _Pragma("unroll") for (int m = 0; m < 4; ++m) _Pragma("unroll") for (int k = 0; k < 2; ++k) dst[m][k] = *(const PG8_LAS bf16x8*)(lds + PG8_SA(b, h) + aoff + m * 2048 + k * 1024); } while (0)
; #define PG8_LDB(dst, b, h) do { _Pragma("unroll") for (int n = 0; n < 2; ++n) _Pragma("unroll") for (int k = 0; k < 2; ++k) dst[n][k] = *(const PG8_LAS bf16x8*)(lds + PG8_SB(b, h) + boff + n * 2048 + k * 1024); } while (0)
; #define PG8_MMA(ai, bj, At, Bt) do { __builtin_amdgcn_s_setprio(1); _Pragma("unroll") for (int m = 0; m < 4; ++m) _Pragma("unroll") for (int n = 0; n < 2; ++n) _Pragma("unroll") for (int k = 0; k < 2; ++k) \
;         acc[ai][bj][m][n] = __builtin_amdgcn_mfma_f32_16x16x32_bf16(Bt[n][k], At[m][k], acc[ai][bj][m][n], 0, 0, 0); __builtin_amdgcn_s_setprio(0); } while (0)
; #define PG8_WAIT_V(n) asm volatile("s_waitcnt vmcnt(" #n ")" ::: "memory")
; #define PG8_WAIT_L(n) asm volatile("s_waitcnt lgkmcnt(" #n ")" ::: "memory")
; #define PG8_BAR __builtin_amdgcn_s_barrier()
; #define PG8_SCHED __builtin_amdgcn_sched_barrier(0)
; template <class Epi, class Sched, bool ALIGN_EPI = false, bool SP2 = false>
; __device__ __forceinline__ void gemm_phase(PG8_LAS unsigned char* lds, const Gemm g, const Sched& S, const Epi& E) {
;     ...
;             PG8_LDB(B0, 0, 0); PG8_LDB(B1, 0, 1); PG8_SCHED; PG8_LDA(At, 0, 0); PG8_STAGE(PG8_SA(1, 1), a1 + hstep, voffA);
;             PG8_WAIT_V(8); PG8_WAIT_L(0); PG8_BAR; PG8_MMA(0, 0, At, B0); PG8_MMA(0, 1, At, B1); PG8_BAR; PG8_SCHED;
;             PG8_LDA(At, 0, 1); PG8_STAGE(PG8_SB(0, 0), b2, voffB); PG8_STAGE(PG8_SB(0, 1), b2 + hstep, voffB); PG8_STAGE(PG8_SA(0, 0), a2, voffA);
;             PG8_WAIT_V(8); PG8_WAIT_L(0); PG8_BAR; PG8_MMA(1, 0, At, B0); PG8_MMA(1, 1, At, B1); PG8_BAR; PG8_SCHED;
.LBB0_441:
	s_add_i32 s61, s44, 2
	s_add_u32 s64, s42, 0x80
	s_addc_u32 s45, s43, 0
	s_add_i32 s66, 0, 0x10000
	s_cmp_eq_u32 s99, s44
	s_cselect_b32 s45, s29, s45
	s_cselect_b32 s44, s28, s64
	s_cselect_b32 s65, s21, s60
	s_cselect_b32 s64, s20, s17
	s_add_i32 s67, 0, 0x14000
	v_add_u32_e32 v142, s66, v228
	v_add_u32_e32 v158, s67, v228
	ds_read_b128 v[130:133], v142
	ds_read_b128 v[134:137], v142 offset:1024
	ds_read_b128 v[138:141], v142 offset:2048
	ds_read_b128 v[142:145], v142 offset:3072
	ds_read_b128 v[146:149], v158
	ds_read_b128 v[150:153], v158 offset:1024
	ds_read_b128 v[154:157], v158 offset:2048
	ds_read_b128 v[158:161], v158 offset:3072
	v_lshl_add_u64 v[206:207], s[42:43], 0, v[190:191]
	s_add_i32 m0, s93, 0xc000
	ds_read_b128 v[162:165], v230
	ds_read_b128 v[166:169], v230 offset:1024
	ds_read_b128 v[170:173], v230 offset:2048
	ds_read_b128 v[174:177], v230 offset:3072
	ds_read_b128 v[178:181], v230 offset:4096
	ds_read_b128 v[194:197], v230 offset:5120
	ds_read_b128 v[198:201], v230 offset:6144
	ds_read_b128 v[202:205], v230 offset:7168
	global_load_lds_dwordx4 v[206:207], off
	v_lshl_add_u64 v[206:207], s[42:43], 0, v[192:193]
	s_add_i32 m0, s93, 0xe000
	s_nop 0
	global_load_lds_dwordx4 v[206:207], off
	s_waitcnt vmcnt(8)
	s_waitcnt lgkmcnt(0)
	s_barrier
	s_setprio 1
	v_mfma_f32_16x16x32_bf16 v[126:129], v[130:133], v[162:165], v[126:129]
	v_mfma_f32_16x16x32_bf16 v[122:125], v[138:141], v[162:165], v[122:125]
	v_mfma_f32_16x16x32_bf16 v[110:113], v[130:133], v[170:173], v[110:113]
	v_mfma_f32_16x16x32_bf16 v[102:105], v[138:141], v[170:173], v[102:105]
	v_mfma_f32_16x16x32_bf16 v[94:97], v[130:133], v[178:181], v[94:97]
	v_mfma_f32_16x16x32_bf16 v[86:89], v[138:141], v[178:181], v[86:89]
	v_mfma_f32_16x16x32_bf16 v[78:81], v[130:133], v[198:201], v[78:81]
	v_mfma_f32_16x16x32_bf16 v[70:73], v[138:141], v[198:201], v[70:73]
	v_mfma_f32_16x16x32_bf16 v[126:129], v[134:137], v[166:169], v[126:129]
	v_mfma_f32_16x16x32_bf16 v[122:125], v[142:145], v[166:169], v[122:125]
	v_mfma_f32_16x16x32_bf16 v[110:113], v[134:137], v[174:177], v[110:113]
	v_mfma_f32_16x16x32_bf16 v[102:105], v[142:145], v[174:177], v[102:105]
	v_mfma_f32_16x16x32_bf16 v[94:97], v[134:137], v[194:197], v[94:97]
	v_mfma_f32_16x16x32_bf16 v[86:89], v[142:145], v[194:197], v[86:89]
	v_mfma_f32_16x16x32_bf16 v[78:81], v[134:137], v[202:205], v[78:81]
	v_mfma_f32_16x16x32_bf16 v[70:73], v[142:145], v[202:205], v[70:73]
	s_setprio 0
	s_setprio 1
	v_mfma_f32_16x16x32_bf16 v[118:121], v[146:149], v[162:165], v[118:121]
	v_mfma_f32_16x16x32_bf16 v[114:117], v[154:157], v[162:165], v[114:117]
	v_mfma_f32_16x16x32_bf16 v[106:109], v[146:149], v[170:173], v[106:109]
	v_mfma_f32_16x16x32_bf16 v[98:101], v[154:157], v[170:173], v[98:101]
	v_mfma_f32_16x16x32_bf16 v[90:93], v[146:149], v[178:181], v[90:93]
	v_mfma_f32_16x16x32_bf16 v[82:85], v[154:157], v[178:181], v[82:85]
	v_mfma_f32_16x16x32_bf16 v[74:77], v[146:149], v[198:201], v[74:77]
	v_mfma_f32_16x16x32_bf16 v[66:69], v[154:157], v[198:201], v[66:69]
	v_mfma_f32_16x16x32_bf16 v[118:121], v[150:153], v[166:169], v[118:121]
	v_mfma_f32_16x16x32_bf16 v[114:117], v[158:161], v[166:169], v[114:117]
	v_mfma_f32_16x16x32_bf16 v[106:109], v[150:153], v[174:177], v[106:109]
	v_mfma_f32_16x16x32_bf16 v[98:101], v[158:161], v[174:177], v[98:101]
	v_mfma_f32_16x16x32_bf16 v[90:93], v[150:153], v[194:197], v[90:93]
	v_mfma_f32_16x16x32_bf16 v[82:85], v[158:161], v[194:197], v[82:85]
	v_mfma_f32_16x16x32_bf16 v[74:77], v[150:153], v[202:205], v[74:77]
	v_mfma_f32_16x16x32_bf16 v[66:69], v[158:161], v[202:205], v[66:69]
	s_setprio 0
	s_barrier
	s_add_i32 s66, s66, s92
	v_lshl_add_u64 v[206:207], s[64:65], 0, v[184:185]
	s_mov_b32 m0, s66
	ds_read_b128 v[162:165], v230 offset:16384
	ds_read_b128 v[166:169], v230 offset:17408
	ds_read_b128 v[170:173], v230 offset:18432
	ds_read_b128 v[174:177], v230 offset:19456
	ds_read_b128 v[178:181], v230 offset:20480
	ds_read_b128 v[194:197], v230 offset:21504
	ds_read_b128 v[198:201], v230 offset:22528
	ds_read_b128 v[202:205], v230 offset:23552
	global_load_lds_dwordx4 v[206:207], off
	s_add_i32 m0, s66, 0x2000
	v_lshl_add_u64 v[208:209], s[64:65], 0, v[188:189]
	s_add_u32 s64, s64, s26
	s_addc_u32 s65, s65, 0
	s_add_i32 s66, s67, s92
	global_load_lds_dwordx4 v[208:209], off
	v_lshl_add_u64 v[210:211], s[64:65], 0, v[184:185]
	s_mov_b32 m0, s66
	v_lshl_add_u64 v[232:233], s[64:65], 0, v[188:189]
	global_load_lds_dwordx4 v[210:211], off
	s_add_i32 m0, s66, 0x2000
	v_lshl_add_u64 v[234:235], s[44:45], 0, v[182:183]
	global_load_lds_dwordx4 v[232:233], off
	s_mov_b32 m0, s93
	v_lshl_add_u64 v[236:237], s[44:45], 0, v[186:187]
	global_load_lds_dwordx4 v[234:235], off
	s_mov_b32 m0, s94
	s_nop 0
	global_load_lds_dwordx4 v[236:237], off
	s_waitcnt vmcnt(8)
	s_waitcnt lgkmcnt(0)
	s_barrier
; #define PG8_STAGE(bufoff, gbase, voff) do { _Pragma("unroll") for (int _i = 0; _i < 2; ++_i) \
;         __builtin_amdgcn_global_load_lds((const unsigned*)((const char*)(gbase) + (voff)[_i]), (PG8_LAS unsigned*)(lds + (bufoff) + ldsw + _i * 8192), 16, 0, 0); } while (0)
; #define PG8_LDA(dst, b, h) do { _Pragma("unroll") for (int m = 0; m < 4; ++m) _Pragma("unroll") for (int k = 0; k < 2; ++k) dst[m][k] = *(const PG8_LAS bf16x8*)(lds + PG8_SA(b, h) + aoff + m * 2048 + k * 1024); } while (0)
; #define PG8_LDB(dst, b, h) do { _Pragma("unroll") for (int n = 0; n < 2; ++n) _Pragma("unroll") for (int k = 0; k < 2; ++k) dst[n][k] = *(const PG8_LAS bf16x8*)(lds + PG8_SB(b, h) + boff + n * 2048 + k * 1024); } while (0)
; #define PG8_MMA(ai, bj, At, Bt) do { __builtin_amdgcn_s_setprio(1); _Pragma("unroll") for (int m = 0; m < 4; ++m) _Pragma("unroll") for (int n = 0; n < 2; ++n) _Pragma("unroll") for (int k = 0; k < 2; ++k) \
;         acc[ai][bj][m][n] = __builtin_amdgcn_mfma_f32_16x16x32_bf16(Bt[n][k], At[m][k], acc[ai][bj][m][n], 0, 0, 0); __builtin_amdgcn_s_setprio(0); } while (0)
; #define PG8_WAIT_V(n) asm volatile("s_waitcnt vmcnt(" #n ")" ::: "memory")
; #define PG8_WAIT_L(n) asm volatile("s_waitcnt lgkmcnt(" #n ")" ::: "memory")
; #define PG8_BAR __builtin_amdgcn_s_barrier()
; #define PG8_SCHED __builtin_amdgcn_sched_barrier(0)
; template <class Epi, class Sched, bool ALIGN_EPI = false, bool SP2 = false>
; __device__ __forceinline__ void gemm_phase(PG8_LAS unsigned char* lds, const Gemm g, const Sched& S, const Epi& E) {
;     ...
;             PG8_WAIT_V(8); PG8_WAIT_L(0); PG8_BAR; PG8_MMA(1, 0, At, B0); PG8_MMA(1, 1, At, B1); PG8_BAR; PG8_SCHED;
;             PG8_LDB(B0, 1, 0); PG8_LDB(B1, 1, 1); PG8_SCHED; PG8_LDA(At, 1, 0); PG8_STAGE(PG8_SA(0, 1), a2 + hstep, voffA);
;             PG8_WAIT_V(8); PG8_WAIT_L(0); PG8_BAR; PG8_MMA(0, 0, At, B0); PG8_MMA(0, 1, At, B1); PG8_BAR; PG8_SCHED;
	s_setprio 1
	v_mfma_f32_16x16x32_bf16 v[62:65], v[130:133], v[162:165], v[62:65]
	v_mfma_f32_16x16x32_bf16 v[54:57], v[138:141], v[162:165], v[54:57]
	v_mfma_f32_16x16x32_bf16 v[46:49], v[130:133], v[170:173], v[46:49]
	v_mfma_f32_16x16x32_bf16 v[38:41], v[138:141], v[170:173], v[38:41]
	v_mfma_f32_16x16x32_bf16 v[30:33], v[130:133], v[178:181], v[30:33]
	v_mfma_f32_16x16x32_bf16 v[22:25], v[138:141], v[178:181], v[22:25]
	v_mfma_f32_16x16x32_bf16 v[14:17], v[130:133], v[198:201], v[14:17]
	v_mfma_f32_16x16x32_bf16 v[6:9], v[138:141], v[198:201], v[6:9]
	v_mfma_f32_16x16x32_bf16 v[62:65], v[134:137], v[166:169], v[62:65]
	v_mfma_f32_16x16x32_bf16 v[54:57], v[142:145], v[166:169], v[54:57]
	v_mfma_f32_16x16x32_bf16 v[46:49], v[134:137], v[174:177], v[46:49]
	v_mfma_f32_16x16x32_bf16 v[38:41], v[142:145], v[174:177], v[38:41]
	v_mfma_f32_16x16x32_bf16 v[30:33], v[134:137], v[194:197], v[30:33]
	v_mfma_f32_16x16x32_bf16 v[22:25], v[142:145], v[194:197], v[22:25]
	v_mfma_f32_16x16x32_bf16 v[14:17], v[134:137], v[202:205], v[14:17]
	v_mfma_f32_16x16x32_bf16 v[6:9], v[142:145], v[202:205], v[6:9]
	s_setprio 0
	s_setprio 1
	v_mfma_f32_16x16x32_bf16 v[58:61], v[146:149], v[162:165], v[58:61]
	v_mfma_f32_16x16x32_bf16 v[50:53], v[154:157], v[162:165], v[50:53]
	v_mfma_f32_16x16x32_bf16 v[42:45], v[146:149], v[170:173], v[42:45]
	v_mfma_f32_16x16x32_bf16 v[34:37], v[154:157], v[170:173], v[34:37]
	v_mfma_f32_16x16x32_bf16 v[26:29], v[146:149], v[178:181], v[26:29]
	v_mfma_f32_16x16x32_bf16 v[18:21], v[154:157], v[178:181], v[18:21]
	v_mfma_f32_16x16x32_bf16 v[10:13], v[146:149], v[198:201], v[10:13]
	v_mfma_f32_16x16x32_bf16 v[2:5], v[154:157], v[198:201], v[2:5]
	v_mfma_f32_16x16x32_bf16 v[58:61], v[150:153], v[166:169], v[58:61]
	v_mfma_f32_16x16x32_bf16 v[50:53], v[158:161], v[166:169], v[50:53]
	v_mfma_f32_16x16x32_bf16 v[42:45], v[150:153], v[174:177], v[42:45]
	v_mfma_f32_16x16x32_bf16 v[34:37], v[158:161], v[174:177], v[34:37]
	v_mfma_f32_16x16x32_bf16 v[26:29], v[150:153], v[194:197], v[26:29]
	v_mfma_f32_16x16x32_bf16 v[18:21], v[158:161], v[194:197], v[18:21]
	v_mfma_f32_16x16x32_bf16 v[10:13], v[150:153], v[202:205], v[10:13]
	v_mfma_f32_16x16x32_bf16 v[2:5], v[158:161], v[202:205], v[2:5]
	s_setprio 0
	s_barrier
	s_add_i32 s64, 0, 0x18000
	s_add_i32 s65, 0, 0x1c000
	v_add_u32_e32 v142, s64, v228
	v_add_u32_e32 v158, s65, v228
	ds_read_b128 v[130:133], v142
	ds_read_b128 v[134:137], v142 offset:1024
	ds_read_b128 v[138:141], v142 offset:2048
	ds_read_b128 v[142:145], v142 offset:3072
	ds_read_b128 v[146:149], v158
	ds_read_b128 v[150:153], v158 offset:1024
	ds_read_b128 v[154:157], v158 offset:2048
	ds_read_b128 v[158:161], v158 offset:3072
	s_add_u32 s44, s44, s26
	s_addc_u32 s45, s45, 0
	s_mov_b32 m0, s95
	v_lshl_add_u64 v[238:239], s[44:45], 0, v[182:183]
	ds_read_b128 v[162:165], v230 offset:32768
	ds_read_b128 v[166:169], v230 offset:33792
	ds_read_b128 v[170:173], v230 offset:34816
	ds_read_b128 v[174:177], v230 offset:35840
	ds_read_b128 v[178:181], v230 offset:36864
	ds_read_b128 v[194:197], v230 offset:37888
	ds_read_b128 v[198:201], v230 offset:38912
	ds_read_b128 v[202:205], v230 offset:39936
	global_load_lds_dwordx4 v[238:239], off
	v_lshl_add_u64 v[238:239], s[44:45], 0, v[186:187]
	s_mov_b32 m0, s96
	s_nop 0
	global_load_lds_dwordx4 v[238:239], off
	s_waitcnt vmcnt(8)
	s_waitcnt lgkmcnt(0)
	s_barrier
	s_setprio 1
	v_mfma_f32_16x16x32_bf16 v[126:129], v[130:133], v[162:165], v[126:129]
	v_mfma_f32_16x16x32_bf16 v[122:125], v[138:141], v[162:165], v[122:125]
	v_mfma_f32_16x16x32_bf16 v[110:113], v[130:133], v[170:173], v[110:113]
	v_mfma_f32_16x16x32_bf16 v[102:105], v[138:141], v[170:173], v[102:105]
	v_mfma_f32_16x16x32_bf16 v[94:97], v[130:133], v[178:181], v[94:97]
	v_mfma_f32_16x16x32_bf16 v[86:89], v[138:141], v[178:181], v[86:89]
	v_mfma_f32_16x16x32_bf16 v[78:81], v[130:133], v[198:201], v[78:81]
	v_mfma_f32_16x16x32_bf16 v[70:73], v[138:141], v[198:201], v[70:73]
	v_mfma_f32_16x16x32_bf16 v[126:129], v[134:137], v[166:169], v[126:129]
	v_mfma_f32_16x16x32_bf16 v[122:125], v[142:145], v[166:169], v[122:125]
	v_mfma_f32_16x16x32_bf16 v[110:113], v[134:137], v[174:177], v[110:113]
	v_mfma_f32_16x16x32_bf16 v[102:105], v[142:145], v[174:177], v[102:105]
	v_mfma_f32_16x16x32_bf16 v[94:97], v[134:137], v[194:197], v[94:97]
	v_mfma_f32_16x16x32_bf16 v[86:89], v[142:145], v[194:197], v[86:89]
	v_mfma_f32_16x16x32_bf16 v[78:81], v[134:137], v[202:205], v[78:81]
	v_mfma_f32_16x16x32_bf16 v[70:73], v[142:145], v[202:205], v[70:73]
	s_setprio 0
	s_setprio 1
	v_mfma_f32_16x16x32_bf16 v[118:121], v[146:149], v[162:165], v[118:121]
	v_mfma_f32_16x16x32_bf16 v[114:117], v[154:157], v[162:165], v[114:117]
	v_mfma_f32_16x16x32_bf16 v[106:109], v[146:149], v[170:173], v[106:109]
	v_mfma_f32_16x16x32_bf16 v[98:101], v[154:157], v[170:173], v[98:101]
	v_mfma_f32_16x16x32_bf16 v[90:93], v[146:149], v[178:181], v[90:93]
	v_mfma_f32_16x16x32_bf16 v[82:85], v[154:157], v[178:181], v[82:85]
	v_mfma_f32_16x16x32_bf16 v[74:77], v[146:149], v[198:201], v[74:77]
	v_mfma_f32_16x16x32_bf16 v[66:69], v[154:157], v[198:201], v[66:69]
	v_mfma_f32_16x16x32_bf16 v[118:121], v[150:153], v[166:169], v[118:121]
	v_mfma_f32_16x16x32_bf16 v[114:117], v[158:161], v[166:169], v[114:117]
	v_mfma_f32_16x16x32_bf16 v[106:109], v[150:153], v[174:177], v[106:109]
	v_mfma_f32_16x16x32_bf16 v[98:101], v[158:161], v[174:177], v[98:101]
	v_mfma_f32_16x16x32_bf16 v[90:93], v[150:153], v[194:197], v[90:93]
	v_mfma_f32_16x16x32_bf16 v[82:85], v[158:161], v[194:197], v[82:85]
	v_mfma_f32_16x16x32_bf16 v[74:77], v[150:153], v[202:205], v[74:77]
	v_mfma_f32_16x16x32_bf16 v[66:69], v[158:161], v[202:205], v[66:69]
	s_setprio 0
	s_barrier
; #define PG8_STAGE(bufoff, gbase, voff) do { _Pragma("unroll") for (int _i = 0; _i < 2; ++_i) \
;         __builtin_amdgcn_global_load_lds((const unsigned*)((const char*)(gbase) + (voff)[_i]), (PG8_LAS unsigned*)(lds + (bufoff) + ldsw + _i * 8192), 16, 0, 0); } while (0)
; #define PG8_LDA(dst, b, h) do { _Pragma("unroll") for (int m = 0; m < 4; ++m) _Pragma("unroll") for (int k = 0; k < 2; ++k) dst[m][k] = *(const PG8_LAS bf16x8*)(lds + PG8_SA(b, h) + aoff + m * 2048 + k * 1024); } while (0)
; #define PG8_MMA(ai, bj, At, Bt) do { __builtin_amdgcn_s_setprio(1); _Pragma("unroll") for (int m = 0; m < 4; ++m) _Pragma("unroll") for (int n = 0; n < 2; ++n) _Pragma("unroll") for (int k = 0; k < 2; ++k) \
;         acc[ai][bj][m][n] = __builtin_amdgcn_mfma_f32_16x16x32_bf16(Bt[n][k], At[m][k], acc[ai][bj][m][n], 0, 0, 0); __builtin_amdgcn_s_setprio(0); } while (0)
; #define PG8_WAIT_V(n) asm volatile("s_waitcnt vmcnt(" #n ")" ::: "memory")
; #define PG8_WAIT_L(n) asm volatile("s_waitcnt lgkmcnt(" #n ")" ::: "memory")
; #define PG8_BAR __builtin_amdgcn_s_barrier()
; #define PG8_SCHED __builtin_amdgcn_sched_barrier(0)
; template <class Epi, class Sched, bool ALIGN_EPI = false, bool SP2 = false>
; __device__ __forceinline__ void gemm_phase(PG8_LAS unsigned char* lds, const Gemm g, const Sched& S, const Epi& E) {
;     ...
;             PG8_LDA(At, 1, 1); PG8_STAGE(PG8_SB(1, 0), b3, voffB); PG8_STAGE(PG8_SB(1, 1), b3 + hstep, voffB); PG8_STAGE(PG8_SA(1, 0), a3, voffA);
;             PG8_WAIT_V(8); PG8_WAIT_L(0); PG8_BAR; PG8_MMA(1, 0, At, B0); PG8_MMA(1, 1, At, B1); PG8_BAR; PG8_SCHED;
;     ...
;         if constexpr (ALIGN_EPI) { if (wr == 0) PG8_BAR; }
;         if constexpr (!Epi::AFTER_DRAIN) { E(acc, cur, wr, wc, fr, fq); S.done(cur); }
	s_add_i32 s44, s64, s92
	v_lshl_add_u64 v[206:207], v[206:207], 0, s[34:35]
	s_mov_b32 m0, s44
	ds_read_b128 v[162:165], v230 offset:49152
	ds_read_b128 v[166:169], v230 offset:50176
	ds_read_b128 v[170:173], v230 offset:51200
	ds_read_b128 v[174:177], v230 offset:52224
	ds_read_b128 v[178:181], v230 offset:53248
	ds_read_b128 v[194:197], v230 offset:54272
	ds_read_b128 v[198:201], v230 offset:55296
	ds_read_b128 v[202:205], v230 offset:56320
	global_load_lds_dwordx4 v[206:207], off
	v_lshl_add_u64 v[206:207], v[208:209], 0, s[34:35]
	s_add_i32 m0, s44, 0x2000
	s_add_i32 s44, s65, s92
	global_load_lds_dwordx4 v[206:207], off
	v_lshl_add_u64 v[206:207], v[210:211], 0, s[34:35]
	s_mov_b32 m0, s44
	s_nop 0
	global_load_lds_dwordx4 v[206:207], off
	v_lshl_add_u64 v[206:207], v[232:233], 0, s[34:35]
	s_add_i32 m0, s44, 0x2000
	s_nop 0
	global_load_lds_dwordx4 v[206:207], off
	v_lshl_add_u64 v[206:207], v[234:235], 0, s[34:35]
	s_mov_b32 m0, s97
	s_nop 0
	global_load_lds_dwordx4 v[206:207], off
	v_lshl_add_u64 v[206:207], v[236:237], 0, s[34:35]
	s_mov_b32 m0, s98
	s_nop 0
	global_load_lds_dwordx4 v[206:207], off
	s_waitcnt vmcnt(8)
	s_waitcnt lgkmcnt(0)
	s_barrier
	s_setprio 1
	v_mfma_f32_16x16x32_bf16 v[62:65], v[130:133], v[162:165], v[62:65]
	v_mfma_f32_16x16x32_bf16 v[54:57], v[138:141], v[162:165], v[54:57]
	v_mfma_f32_16x16x32_bf16 v[46:49], v[130:133], v[170:173], v[46:49]
	v_mfma_f32_16x16x32_bf16 v[38:41], v[138:141], v[170:173], v[38:41]
	v_mfma_f32_16x16x32_bf16 v[30:33], v[130:133], v[178:181], v[30:33]
	v_mfma_f32_16x16x32_bf16 v[22:25], v[138:141], v[178:181], v[22:25]
	v_mfma_f32_16x16x32_bf16 v[14:17], v[130:133], v[198:201], v[14:17]
	v_mfma_f32_16x16x32_bf16 v[6:9], v[138:141], v[198:201], v[6:9]
	v_mfma_f32_16x16x32_bf16 v[62:65], v[134:137], v[166:169], v[62:65]
	v_mfma_f32_16x16x32_bf16 v[54:57], v[142:145], v[166:169], v[54:57]
	v_mfma_f32_16x16x32_bf16 v[46:49], v[134:137], v[174:177], v[46:49]
	v_mfma_f32_16x16x32_bf16 v[38:41], v[142:145], v[174:177], v[38:41]
	v_mfma_f32_16x16x32_bf16 v[30:33], v[134:137], v[194:197], v[30:33]
	v_mfma_f32_16x16x32_bf16 v[22:25], v[142:145], v[194:197], v[22:25]
	v_mfma_f32_16x16x32_bf16 v[14:17], v[134:137], v[202:205], v[14:17]
	v_mfma_f32_16x16x32_bf16 v[6:9], v[142:145], v[202:205], v[6:9]
	s_setprio 0
	s_setprio 1
	v_mfma_f32_16x16x32_bf16 v[58:61], v[146:149], v[162:165], v[58:61]
	v_mfma_f32_16x16x32_bf16 v[50:53], v[154:157], v[162:165], v[50:53]
	v_mfma_f32_16x16x32_bf16 v[42:45], v[146:149], v[170:173], v[42:45]
	v_mfma_f32_16x16x32_bf16 v[34:37], v[154:157], v[170:173], v[34:37]
	v_mfma_f32_16x16x32_bf16 v[26:29], v[146:149], v[178:181], v[26:29]
	v_mfma_f32_16x16x32_bf16 v[18:21], v[154:157], v[178:181], v[18:21]
	v_mfma_f32_16x16x32_bf16 v[10:13], v[146:149], v[198:201], v[10:13]
	v_mfma_f32_16x16x32_bf16 v[2:5], v[154:157], v[198:201], v[2:5]
	v_mfma_f32_16x16x32_bf16 v[58:61], v[150:153], v[166:169], v[58:61]
	v_mfma_f32_16x16x32_bf16 v[50:53], v[158:161], v[166:169], v[50:53]
	v_mfma_f32_16x16x32_bf16 v[42:45], v[150:153], v[174:177], v[42:45]
	v_mfma_f32_16x16x32_bf16 v[34:37], v[158:161], v[174:177], v[34:37]
	v_mfma_f32_16x16x32_bf16 v[26:29], v[150:153], v[194:197], v[26:29]
	v_mfma_f32_16x16x32_bf16 v[18:21], v[158:161], v[194:197], v[18:21]
	v_mfma_f32_16x16x32_bf16 v[10:13], v[150:153], v[202:205], v[10:13]
	v_mfma_f32_16x16x32_bf16 v[2:5], v[158:161], v[202:205], v[2:5]
	s_setprio 0
	s_barrier
	s_add_u32 s42, s42, 0x100
	s_addc_u32 s43, s43, 0
	s_add_u32 s17, s17, 0x100
	s_addc_u32 s60, s60, 0
	s_cmp_ge_u32 s61, s4
	s_mov_b32 s44, s61
	s_cbranch_scc0 .LBB0_441
	s_and_b64 vcc, exec, s[36:37]
	s_cbranch_vccz .LBB0_445
	s_barrier
	s_cmp_lt_i32 s0, 2
	s_mov_b64 s[42:43], -1
	s_cbranch_scc0 .LBB0_446
